# cache policy: residual stream (h) stores marked non-temporal (re-read only much later by the same CU)
# baseline (speedup 1.0000x reference)
; __device__ __forceinline__ void epi_all_run(const void* Pk_, int l, int s, const f32x4 (&acc)[2][2][4][2], const pg8::Unit& u, int wr, int wc, int fr, int fq) {
;     ...
;             const float* MOD = (const float*)(ws + WS_MOD);
;             const int gidx = (s == 1) ? 2 : (s == 4 ? 5 : 8);
;             const float* base = (l == 0 && s == 1) ? A.x : A.out; float* out = A.out;
;             const float* gp = MOD + (size_t)(l * 4 + b) * NMODC + gidx * DM; const float scale = (s == 4) ? 1.0f : 0.5f;
;             const int nsite = 3 * l + (s == 1 ? 1 : (s == 4 ? 2 : 3));
;             const int col0 = u.pn * 256 + wc * 32 + 8 * fq;
;             float* slots = (float*)(ws + WS_RSP) + (size_t)nsite * M * 16;
;             f32x4 gv[2][2];
; #pragma unroll
;             for (int bj = 0; bj < 2; ++bj)
; #pragma unroll
;                 for (int n = 0; n < 2; ++n) gv[bj][n] = *(const f32x4*)(gp + col0 + bj * 128 + n * 4) * scale;
;             f32x4 bb[2][2][2];
; #pragma unroll
;             for (int bj = 0; bj < 2; ++bj)
; #pragma unroll
;                 for (int n = 0; n < 2; ++n) bb[0][bj][n] = *(const f32x4*)(base + (size_t)row0 * DM + col0 + bj * 128 + n * 4);
; #pragma unroll
;             for (int g = 0; g < 8; ++g) {
;                 const int ai = g >> 2, m = g & 3, row = row0 + ai * 128 + m * 16;
;                 if (g < 7) { const int rown = row0 + ((g + 1) >> 2) * 128 + ((g + 1) & 3) * 16;
; #pragma unroll
;                     for (int bj = 0; bj < 2; ++bj)
; #pragma unroll
;                         for (int n = 0; n < 2; ++n) bb[(g + 1) & 1][bj][n] = *(const f32x4*)(base + (size_t)rown * DM + col0 + bj * 128 + n * 4); }
;                 float ss = 0.f;
; #pragma unroll
;                 for (int bj = 0; bj < 2; ++bj)
; #pragma unroll
;                     for (int n = 0; n < 2; ++n) {
;                         const f32x4 h = bb[g & 1][bj][n] + gv[bj][n] * acc[ai][bj][m][n];
;                         *(f32x4*)(out + (size_t)row * DM + col0 + bj * 128 + n * 4) = h;
;                         ss += (h[0] * h[0] + h[1] * h[1]) + (h[2] * h[2] + h[3] * h[3]);
;                     }
;                 if (nsite < 3 * DEPTH) {
;                     ss += shx(ss, 16); ss += shx(ss, 32);
;                     if (fq == 0) __hip_atomic_store(slots + ((size_t)u.pn * M + row) * 4 + wc, ss, __ATOMIC_RELAXED, __HIP_MEMORY_SCOPE_AGENT);
.LBB0_90:
	s_andn2_b64 vcc, exec, s[46:47]
	v_or_b32_e32 v186, 16, v184
	s_cbranch_vccnz .LBB0_125
	s_ashr_i32 s20, s31, 4
	s_cmp_eq_u32 s75, 0
	s_cselect_b64 s[38:39], -1, 0
	s_cmp_eq_u32 s76, 4
	s_cselect_b64 s[46:47], -1, 0
	v_cndmask_b32_e64 v168, 0.5, 1.0, s[46:47]
	s_and_b64 s[46:47], s[46:47], exec
	s_cselect_b32 s31, s93, 0x2000
	s_cselect_b32 s50, 2, 3
	s_cmp_eq_u32 s76, 1
	s_cselect_b64 s[46:47], -1, 0
	s_and_b64 s[48:49], s[46:47], exec
	s_cselect_b32 s31, 0x800, s31
	s_cselect_b32 s48, 1, s50
	s_and_b64 s[38:39], s[38:39], s[46:47]
	s_and_b64 s[38:39], s[38:39], exec
	s_cselect_b32 s38, 0, 0xc0
	s_add_u32 s38, s4, s38
	s_addc_u32 s39, s5, 0
	s_lshl_b32 s46, s75, 2
	s_add_i32 s20, s46, s20
	s_mul_hi_i32 s46, s20, 0x9000
	s_mul_i32 s20, s20, 0x9000
	s_waitcnt lgkmcnt(0)
	s_add_u32 s20, s34, s20
	s_addc_u32 s47, s35, s46
	s_lshl_b32 s31, s31, 2
	v_lshl_or_b32 v130, s30, 8, v228
	s_add_u32 s46, s20, s31
	v_ashrrev_i32_e32 v131, 31, v130
	s_load_dwordx2 s[38:39], s[38:39], 0x0
	s_nop 0
	s_load_dwordx2 s[4:5], s[4:5], 0xc0
	s_addc_u32 s47, s47, 0
	v_lshlrev_b64 v[188:189], 2, v[130:131]
	v_lshl_add_u64 v[130:131], s[46:47], 0, v[188:189]
	s_mov_b64 s[46:47], 0x10000
	s_mov_b32 s20, 0x10000
	v_lshl_add_u64 v[132:133], v[130:131], 0, s[46:47]
	v_add_co_u32_e32 v130, vcc, s20, v130
	v_ashrrev_i32_e32 v185, 31, v184
	s_nop 0
	v_addc_co_u32_e32 v131, vcc, 0, v131, vcc
	v_lshlrev_b64 v[190:191], 12, v[184:185]
	v_ashrrev_i32_e32 v187, 31, v186
	global_load_dwordx4 v[142:145], v[130:131], off
	global_load_dwordx4 v[150:153], v[132:133], off offset:528
	global_load_dwordx4 v[154:157], v[132:133], off offset:16
	global_load_dwordx4 v[158:161], v[132:133], off offset:512
	s_waitcnt lgkmcnt(0)
	v_lshl_add_u64 v[130:131], s[38:39], 0, v[190:191]
	v_lshl_add_u64 v[206:207], s[38:39], 0, v[188:189]
	v_lshlrev_b64 v[166:167], 12, v[186:187]
	v_lshl_add_u64 v[130:131], v[130:131], 0, v[188:189]
	v_lshl_add_u64 v[134:135], v[206:207], 0, v[166:167]
	global_load_dwordx4 v[162:165], v[130:131], off
	global_load_dwordx4 v[208:211], v[130:131], off offset:16
	global_load_dwordx4 v[212:215], v[130:131], off offset:528
	global_load_dwordx4 v[230:233], v[130:131], off offset:512
	global_load_dwordx4 v[138:141], v[134:135], off offset:16
	global_load_dwordx4 v[146:149], v[134:135], off
	s_nop 0
	global_load_dwordx4 v[130:133], v[134:135], off offset:528
	s_nop 0
	global_load_dwordx4 v[134:137], v[134:135], off offset:512
	s_mul_i32 s75, s75, 3
	s_add_i32 s48, s48, s75
	s_ashr_i32 s49, s48, 31
	v_lshl_add_u64 v[200:201], s[4:5], 0, v[188:189]
	s_lshl_b64 s[4:5], s[48:49], 20
	s_add_u32 s4, s34, s4
	s_addc_u32 s5, s35, s5
	s_add_u32 s20, s4, 0xed00000
	s_addc_u32 s46, s5, 0
	v_lshl_add_u64 v[234:235], v[200:201], 0, v[190:191]
	s_cmp_lt_i32 s48, 6
	s_cselect_b64 s[38:39], -1, 0
	s_cmp_gt_i32 s48, 5
	s_waitcnt vmcnt(0)
	v_pk_mul_f32 v[202:203], v[168:169], v[144:145] op_sel_hi:[0,1]
	v_pk_mul_f32 v[204:205], v[168:169], v[142:143] op_sel_hi:[0,1]
	v_pk_mul_f32 v[198:199], v[168:169], v[156:157] op_sel_hi:[0,1]
	v_pk_mul_f32 v[196:197], v[168:169], v[154:155] op_sel_hi:[0,1]
	v_pk_mul_f32 v[192:193], v[168:169], v[160:161] op_sel_hi:[0,1]
	v_pk_mul_f32 v[194:195], v[168:169], v[158:159] op_sel_hi:[0,1]
	v_pk_mul_f32 v[190:191], v[168:169], v[152:153] op_sel_hi:[0,1]
	v_pk_mul_f32 v[188:189], v[168:169], v[150:151] op_sel_hi:[0,1]
	v_pk_fma_f32 v[128:129], v[128:129], v[202:203], v[164:165]
	v_pk_fma_f32 v[126:127], v[126:127], v[204:205], v[162:163]
	v_pk_fma_f32 v[124:125], v[124:125], v[198:199], v[210:211]
	v_pk_fma_f32 v[122:123], v[122:123], v[196:197], v[208:209]
	v_pk_fma_f32 v[120:121], v[120:121], v[192:193], v[232:233]
	v_pk_fma_f32 v[118:119], v[118:119], v[194:195], v[230:231]
	v_pk_fma_f32 v[116:117], v[116:117], v[190:191], v[214:215]
	v_pk_fma_f32 v[114:115], v[114:115], v[188:189], v[212:213]
	global_store_dwordx4 v[234:235], v[126:129], off nt
	global_store_dwordx4 v[234:235], v[122:125], off offset:16 nt
	global_store_dwordx4 v[234:235], v[118:121], off offset:512 nt
	global_store_dwordx4 v[234:235], v[114:117], off offset:528 nt
	s_cbranch_scc1 .LBB0_95
	v_mul_f32_e32 v143, v127, v127
	v_fmac_f32_e32 v143, v126, v126
	v_mul_f32_e32 v142, v129, v129
	v_fmac_f32_e32 v142, v128, v128
	v_add_f32_e32 v142, v143, v142
	v_mul_f32_e32 v143, v123, v123
	v_mul_f32_e32 v144, v125, v125
	v_fmac_f32_e32 v143, v122, v122
	v_fmac_f32_e32 v144, v124, v124
	v_add_f32_e32 v143, v143, v144
	v_add_f32_e32 v142, v142, v143
	v_mul_f32_e32 v143, v119, v119
	v_mul_f32_e32 v144, v121, v121
	v_fmac_f32_e32 v143, v118, v118
	v_fmac_f32_e32 v144, v120, v120
	v_add_f32_e32 v143, v143, v144
	v_add_f32_e32 v142, v142, v143
	v_mul_f32_e32 v143, v115, v115
	v_mul_f32_e32 v144, v117, v117
	v_fmac_f32_e32 v143, v114, v114
	v_fmac_f32_e32 v144, v116, v116
	v_add_f32_e32 v143, v143, v144
	v_add_f32_e32 v142, v142, v143
	v_mov_b32_e32 v170, v142
; __device__ __forceinline__ float shx(float v, int o) { const int idx = (((int)otid() & 63) ^ o) << 2; return __builtin_bit_cast(float, __builtin_amdgcn_ds_bpermute(idx, __builtin_bit_cast(int, v))); }
; __device__ __forceinline__ void epi_all_run(const void* Pk_, int l, int s, const f32x4 (&acc)[2][2][4][2], const pg8::Unit& u, int wr, int wc, int fr, int fq) {
;     ...
;             for (int g = 0; g < 8; ++g) {
;                 const int ai = g >> 2, m = g & 3, row = row0 + ai * 128 + m * 16;
;                 if (g < 7) { const int rown = row0 + ((g + 1) >> 2) * 128 + ((g + 1) & 3) * 16;
; #pragma unroll
;                     for (int bj = 0; bj < 2; ++bj)
; #pragma unroll
;                         for (int n = 0; n < 2; ++n) bb[(g + 1) & 1][bj][n] = *(const f32x4*)(base + (size_t)rown * DM + col0 + bj * 128 + n * 4); }
;                 float ss = 0.f;
; #pragma unroll
;                 for (int bj = 0; bj < 2; ++bj)
; #pragma unroll
;                     for (int n = 0; n < 2; ++n) {
;                         const f32x4 h = bb[g & 1][bj][n] + gv[bj][n] * acc[ai][bj][m][n];
;                         *(f32x4*)(out + (size_t)row * DM + col0 + bj * 128 + n * 4) = h;
;                         ss += (h[0] * h[0] + h[1] * h[1]) + (h[2] * h[2] + h[3] * h[3]);
;                     }
;                 if (nsite < 3 * DEPTH) {
;                     ss += shx(ss, 16); ss += shx(ss, 32);
;                     if (fq == 0) __hip_atomic_store(slots + ((size_t)u.pn * M + row) * 4 + wc, ss, __ATOMIC_RELAXED, __HIP_MEMORY_SCOPE_AGENT);
.LBB0_94:
.LBB0_95:
	v_or_b32_e32 v208, 32, v184
	v_ashrrev_i32_e32 v209, 31, v208
	v_lshlrev_b64 v[212:213], 12, v[208:209]
	v_lshl_add_u64 v[150:151], v[206:207], 0, v[212:213]
	global_load_dwordx4 v[154:157], v[150:151], off offset:16
	global_load_dwordx4 v[162:165], v[150:151], off
	s_waitcnt lgkmcnt(0)
	global_load_dwordx4 v[142:145], v[150:151], off offset:528
	s_nop 0
	global_load_dwordx4 v[150:153], v[150:151], off offset:512
	v_cndmask_b32_e64 v160, 0, 1, s[38:39]
	v_lshl_add_u64 v[158:159], v[200:201], 0, v[166:167]
	v_pk_fma_f32 v[112:113], v[112:113], v[202:203], v[148:149]
	v_pk_fma_f32 v[110:111], v[110:111], v[204:205], v[146:147]
	v_pk_fma_f32 v[108:109], v[108:109], v[198:199], v[140:141]
	v_pk_fma_f32 v[106:107], v[106:107], v[196:197], v[138:139]
	v_pk_fma_f32 v[104:105], v[104:105], v[192:193], v[136:137]
	v_pk_fma_f32 v[102:103], v[102:103], v[194:195], v[134:135]
	v_pk_fma_f32 v[100:101], v[100:101], v[190:191], v[132:133]
	v_pk_fma_f32 v[98:99], v[98:99], v[188:189], v[130:131]
	v_cmp_ne_u32_e64 s[4:5], 1, v160
	s_andn2_b64 vcc, exec, s[38:39]
	global_store_dwordx4 v[158:159], v[110:113], off nt
	global_store_dwordx4 v[158:159], v[106:109], off offset:16 nt
	global_store_dwordx4 v[158:159], v[102:105], off offset:512 nt
	global_store_dwordx4 v[158:159], v[98:101], off offset:528 nt
	s_cbranch_vccnz .LBB0_99
	v_mul_f32_e32 v147, v111, v111
	v_mul_f32_e32 v139, v107, v107
	v_mul_f32_e32 v131, v99, v99
	v_fmac_f32_e32 v147, v110, v110
	v_mul_f32_e32 v146, v113, v113
	v_fmac_f32_e32 v139, v106, v106
	v_mul_f32_e32 v138, v109, v109
	v_mul_f32_e32 v135, v103, v103
	v_fmac_f32_e32 v131, v98, v98
	v_mul_f32_e32 v130, v101, v101
	v_fmac_f32_e32 v146, v112, v112
	v_fmac_f32_e32 v138, v108, v108
	v_fmac_f32_e32 v135, v102, v102
	v_mul_f32_e32 v134, v105, v105
	v_fmac_f32_e32 v130, v100, v100
	v_add_f32_e32 v146, v147, v146
	v_add_f32_e32 v138, v139, v138
	v_fmac_f32_e32 v134, v104, v104
	v_add_f32_e32 v130, v131, v130
	v_add_f32_e32 v138, v146, v138
	v_add_f32_e32 v134, v135, v134
	v_add_f32_e32 v134, v138, v134
	v_add_f32_e32 v130, v134, v130
	v_mov_b32_e32 v171, v130
.LBB0_98:
.LBB0_99:
	v_or_b32_e32 v210, 48, v184
	v_ashrrev_i32_e32 v211, 31, v210
	v_lshlrev_b64 v[214:215], 12, v[210:211]
	v_lshl_add_u64 v[134:135], v[206:207], 0, v[214:215]
	global_load_dwordx4 v[158:161], v[134:135], off offset:16
	global_load_dwordx4 v[166:169], v[134:135], off
	s_waitcnt lgkmcnt(0)
	global_load_dwordx4 v[130:133], v[134:135], off offset:528
	global_load_dwordx4 v[146:149], v[134:135], off offset:512
	v_lshl_add_u64 v[212:213], v[200:201], 0, v[212:213]
	s_waitcnt vmcnt(10)
	v_pk_fma_f32 v[96:97], v[96:97], v[202:203], v[164:165]
	v_pk_fma_f32 v[94:95], v[94:95], v[204:205], v[162:163]
	v_pk_fma_f32 v[92:93], v[92:93], v[198:199], v[156:157]
	v_pk_fma_f32 v[90:91], v[90:91], v[196:197], v[154:155]
	s_waitcnt vmcnt(8)
	v_pk_fma_f32 v[88:89], v[88:89], v[192:193], v[152:153]
	v_pk_fma_f32 v[86:87], v[86:87], v[194:195], v[150:151]
	v_pk_fma_f32 v[84:85], v[84:85], v[190:191], v[144:145]
	v_pk_fma_f32 v[82:83], v[82:83], v[188:189], v[142:143]
	s_and_b64 vcc, exec, s[4:5]
	global_store_dwordx4 v[212:213], v[94:97], off nt
	global_store_dwordx4 v[212:213], v[90:93], off offset:16 nt
	global_store_dwordx4 v[212:213], v[86:89], off offset:512 nt
	global_store_dwordx4 v[212:213], v[82:85], off offset:528 nt
	s_cbranch_vccnz .LBB0_103
	v_mul_f32_e32 v135, v95, v95
	v_fmac_f32_e32 v135, v94, v94
	v_mul_f32_e32 v134, v97, v97
	v_fmac_f32_e32 v134, v96, v96
	v_add_f32_e32 v134, v135, v134
	v_mul_f32_e32 v135, v91, v91
	v_mul_f32_e32 v136, v93, v93
	v_fmac_f32_e32 v135, v90, v90
	v_fmac_f32_e32 v136, v92, v92
	v_add_f32_e32 v135, v135, v136
	v_add_f32_e32 v134, v134, v135
	v_mul_f32_e32 v135, v87, v87
	v_mul_f32_e32 v136, v89, v89
	v_fmac_f32_e32 v135, v86, v86
	v_fmac_f32_e32 v136, v88, v88
	v_add_f32_e32 v135, v135, v136
	v_add_f32_e32 v134, v134, v135
	v_mul_f32_e32 v135, v83, v83
	v_mul_f32_e32 v136, v85, v85
	v_fmac_f32_e32 v135, v82, v82
	v_fmac_f32_e32 v136, v84, v84
	v_add_f32_e32 v135, v135, v136
	v_add_f32_e32 v134, v134, v135
	v_mov_b32_e32 v172, v134
.LBB0_102:
.LBB0_103:
	v_add_u32_e32 v208, 0x80, v184
	v_ashrrev_i32_e32 v209, 31, v208
	v_lshlrev_b64 v[212:213], 12, v[208:209]
	v_lshl_add_u64 v[138:139], v[206:207], 0, v[212:213]
	global_load_dwordx4 v[150:153], v[138:139], off offset:16
	global_load_dwordx4 v[162:165], v[138:139], off
	s_waitcnt lgkmcnt(0)
	global_load_dwordx4 v[134:137], v[138:139], off offset:528
	s_nop 0
	global_load_dwordx4 v[138:141], v[138:139], off offset:512
	v_lshl_add_u64 v[214:215], v[200:201], 0, v[214:215]
	s_waitcnt vmcnt(10)
	v_pk_fma_f32 v[80:81], v[80:81], v[202:203], v[168:169]
	v_pk_fma_f32 v[78:79], v[78:79], v[204:205], v[166:167]
	v_pk_fma_f32 v[76:77], v[76:77], v[198:199], v[160:161]
	v_pk_fma_f32 v[74:75], v[74:75], v[196:197], v[158:159]
	s_waitcnt vmcnt(8)
	v_pk_fma_f32 v[72:73], v[72:73], v[192:193], v[148:149]
	v_pk_fma_f32 v[70:71], v[70:71], v[194:195], v[146:147]
	v_pk_fma_f32 v[68:69], v[68:69], v[190:191], v[132:133]
	v_pk_fma_f32 v[66:67], v[66:67], v[188:189], v[130:131]
	s_and_b64 vcc, exec, s[4:5]
	global_store_dwordx4 v[214:215], v[78:81], off nt
	global_store_dwordx4 v[214:215], v[74:77], off offset:16 nt
	global_store_dwordx4 v[214:215], v[70:73], off offset:512 nt
	global_store_dwordx4 v[214:215], v[66:69], off offset:528 nt
	s_cbranch_vccnz .LBB0_107
	v_mul_f32_e32 v143, v79, v79
	v_fmac_f32_e32 v143, v78, v78
	v_mul_f32_e32 v142, v81, v81
	v_fmac_f32_e32 v142, v80, v80
	v_add_f32_e32 v142, v143, v142
	v_mul_f32_e32 v143, v75, v75
	v_mul_f32_e32 v144, v77, v77
	v_fmac_f32_e32 v143, v74, v74
	v_fmac_f32_e32 v144, v76, v76
	v_mul_f32_e32 v131, v67, v67
	v_add_f32_e32 v143, v143, v144
	v_fmac_f32_e32 v131, v66, v66
	v_mul_f32_e32 v130, v69, v69
	v_add_f32_e32 v142, v142, v143
	v_mul_f32_e32 v143, v71, v71
	v_mul_f32_e32 v144, v73, v73
	v_fmac_f32_e32 v130, v68, v68
	v_fmac_f32_e32 v143, v70, v70
	v_fmac_f32_e32 v144, v72, v72
	v_add_f32_e32 v130, v131, v130
	v_add_f32_e32 v143, v143, v144
	v_add_f32_e32 v142, v142, v143
	v_add_f32_e32 v130, v142, v130
	v_mov_b32_e32 v173, v130
; __device__ __forceinline__ float shx(float v, int o) { const int idx = (((int)otid() & 63) ^ o) << 2; return __builtin_bit_cast(float, __builtin_amdgcn_ds_bpermute(idx, __builtin_bit_cast(int, v))); }
; __device__ __forceinline__ void epi_all_run(const void* Pk_, int l, int s, const f32x4 (&acc)[2][2][4][2], const pg8::Unit& u, int wr, int wc, int fr, int fq) {
;     ...
;             for (int g = 0; g < 8; ++g) {
;                 const int ai = g >> 2, m = g & 3, row = row0 + ai * 128 + m * 16;
;                 if (g < 7) { const int rown = row0 + ((g + 1) >> 2) * 128 + ((g + 1) & 3) * 16;
; #pragma unroll
;                     for (int bj = 0; bj < 2; ++bj)
; #pragma unroll
;                         for (int n = 0; n < 2; ++n) bb[(g + 1) & 1][bj][n] = *(const f32x4*)(base + (size_t)rown * DM + col0 + bj * 128 + n * 4); }
;                 float ss = 0.f;
; #pragma unroll
;                 for (int bj = 0; bj < 2; ++bj)
; #pragma unroll
;                     for (int n = 0; n < 2; ++n) {
;                         const f32x4 h = bb[g & 1][bj][n] + gv[bj][n] * acc[ai][bj][m][n];
;                         *(f32x4*)(out + (size_t)row * DM + col0 + bj * 128 + n * 4) = h;
;                         ss += (h[0] * h[0] + h[1] * h[1]) + (h[2] * h[2] + h[3] * h[3]);
;                     }
;                 if (nsite < 3 * DEPTH) {
;                     ss += shx(ss, 16); ss += shx(ss, 32);
;                     if (fq == 0) __hip_atomic_store(slots + ((size_t)u.pn * M + row) * 4 + wc, ss, __ATOMIC_RELAXED, __HIP_MEMORY_SCOPE_AGENT);
.LBB0_106:
.LBB0_107:
	v_or_b32_e32 v210, 16, v208
	v_ashrrev_i32_e32 v211, 31, v210
	v_lshlrev_b64 v[214:215], 12, v[210:211]
	v_lshl_add_u64 v[142:143], v[206:207], 0, v[214:215]
	global_load_dwordx4 v[154:157], v[142:143], off offset:16
	global_load_dwordx4 v[166:169], v[142:143], off
	s_waitcnt lgkmcnt(0)
	global_load_dwordx4 v[130:133], v[142:143], off offset:528
	s_nop 0
	global_load_dwordx4 v[142:145], v[142:143], off offset:512
	v_lshl_add_u64 v[158:159], v[200:201], 0, v[212:213]
	s_waitcnt vmcnt(10)
	v_pk_fma_f32 v[64:65], v[64:65], v[202:203], v[164:165]
	v_pk_fma_f32 v[62:63], v[62:63], v[204:205], v[162:163]
	v_pk_fma_f32 v[60:61], v[60:61], v[198:199], v[152:153]
	v_pk_fma_f32 v[58:59], v[58:59], v[196:197], v[150:151]
	s_waitcnt vmcnt(8)
	v_pk_fma_f32 v[56:57], v[56:57], v[192:193], v[140:141]
	v_pk_fma_f32 v[54:55], v[54:55], v[194:195], v[138:139]
	v_pk_fma_f32 v[52:53], v[52:53], v[190:191], v[136:137]
	v_pk_fma_f32 v[50:51], v[50:51], v[188:189], v[134:135]
	s_and_b64 vcc, exec, s[4:5]
	global_store_dwordx4 v[158:159], v[62:65], off nt
	global_store_dwordx4 v[158:159], v[58:61], off offset:16 nt
	global_store_dwordx4 v[158:159], v[54:57], off offset:512 nt
	global_store_dwordx4 v[158:159], v[50:53], off offset:528 nt
	s_cbranch_vccnz .LBB0_111
	v_mul_f32_e32 v147, v63, v63
	v_fmac_f32_e32 v147, v62, v62
	v_mul_f32_e32 v146, v65, v65
	v_fmac_f32_e32 v146, v64, v64
	v_mul_f32_e32 v135, v51, v51
	v_add_f32_e32 v146, v147, v146
	v_mul_f32_e32 v147, v59, v59
	v_mul_f32_e32 v148, v61, v61
	v_mul_f32_e32 v139, v55, v55
	v_fmac_f32_e32 v135, v50, v50
	v_mul_f32_e32 v134, v53, v53
	v_fmac_f32_e32 v147, v58, v58
	v_fmac_f32_e32 v148, v60, v60
	v_fmac_f32_e32 v139, v54, v54
	v_mul_f32_e32 v138, v57, v57
	v_fmac_f32_e32 v134, v52, v52
	v_add_f32_e32 v147, v147, v148
	v_fmac_f32_e32 v138, v56, v56
	v_add_f32_e32 v134, v135, v134
	v_add_f32_e32 v146, v146, v147
	v_add_f32_e32 v138, v139, v138
	v_add_f32_e32 v138, v146, v138
	v_add_f32_e32 v134, v138, v134
	v_mov_b32_e32 v174, v134
.LBB0_110:
.LBB0_111:
	v_or_b32_e32 v162, 32, v208
	v_ashrrev_i32_e32 v163, 31, v162
	v_lshlrev_b64 v[212:213], 12, v[162:163]
	v_lshl_add_u64 v[138:139], v[206:207], 0, v[212:213]
	global_load_dwordx4 v[146:149], v[138:139], off offset:16
	global_load_dwordx4 v[158:161], v[138:139], off
	s_waitcnt lgkmcnt(0)
	global_load_dwordx4 v[134:137], v[138:139], off offset:528
	s_nop 0
	global_load_dwordx4 v[138:141], v[138:139], off offset:512
	v_lshl_add_u64 v[164:165], v[200:201], 0, v[214:215]
	s_waitcnt vmcnt(10)
	v_pk_fma_f32 v[48:49], v[48:49], v[202:203], v[168:169]
	v_pk_fma_f32 v[46:47], v[46:47], v[204:205], v[166:167]
	v_pk_fma_f32 v[44:45], v[44:45], v[198:199], v[156:157]
	v_pk_fma_f32 v[42:43], v[42:43], v[196:197], v[154:155]
	s_waitcnt vmcnt(8)
	v_pk_fma_f32 v[40:41], v[40:41], v[192:193], v[144:145]
	v_pk_fma_f32 v[38:39], v[38:39], v[194:195], v[142:143]
	v_pk_fma_f32 v[36:37], v[36:37], v[190:191], v[132:133]
	v_pk_fma_f32 v[34:35], v[34:35], v[188:189], v[130:131]
	s_and_b64 vcc, exec, s[4:5]
	global_store_dwordx4 v[164:165], v[46:49], off nt
	global_store_dwordx4 v[164:165], v[42:45], off offset:16 nt
	global_store_dwordx4 v[164:165], v[38:41], off offset:512 nt
	global_store_dwordx4 v[164:165], v[34:37], off offset:528 nt
	s_cbranch_vccnz .LBB0_115
	v_mul_f32_e32 v151, v47, v47
	v_fmac_f32_e32 v151, v46, v46
	v_mul_f32_e32 v150, v49, v49
	v_fmac_f32_e32 v150, v48, v48
	v_mul_f32_e32 v131, v35, v35
	v_add_f32_e32 v150, v151, v150
	v_mul_f32_e32 v151, v43, v43
	v_mul_f32_e32 v152, v45, v45
	v_mul_f32_e32 v143, v39, v39
	v_fmac_f32_e32 v131, v34, v34
	v_mul_f32_e32 v130, v37, v37
	v_fmac_f32_e32 v151, v42, v42
	v_fmac_f32_e32 v152, v44, v44
	v_fmac_f32_e32 v143, v38, v38
	v_mul_f32_e32 v142, v41, v41
	v_fmac_f32_e32 v130, v36, v36
	v_add_f32_e32 v151, v151, v152
	v_fmac_f32_e32 v142, v40, v40
	v_add_f32_e32 v130, v131, v130
	v_add_f32_e32 v150, v150, v151
	v_add_f32_e32 v142, v143, v142
	v_add_f32_e32 v142, v150, v142
	v_add_f32_e32 v130, v142, v130
	v_mov_b32_e32 v175, v130
; __device__ __forceinline__ float shx(float v, int o) { const int idx = (((int)otid() & 63) ^ o) << 2; return __builtin_bit_cast(float, __builtin_amdgcn_ds_bpermute(idx, __builtin_bit_cast(int, v))); }
; __device__ __forceinline__ void epi_all_run(const void* Pk_, int l, int s, const f32x4 (&acc)[2][2][4][2], const pg8::Unit& u, int wr, int wc, int fr, int fq) {
;     ...
;             for (int g = 0; g < 8; ++g) {
;                 const int ai = g >> 2, m = g & 3, row = row0 + ai * 128 + m * 16;
;                 if (g < 7) { const int rown = row0 + ((g + 1) >> 2) * 128 + ((g + 1) & 3) * 16;
; #pragma unroll
;                     for (int bj = 0; bj < 2; ++bj)
; #pragma unroll
;                         for (int n = 0; n < 2; ++n) bb[(g + 1) & 1][bj][n] = *(const f32x4*)(base + (size_t)rown * DM + col0 + bj * 128 + n * 4); }
;                 float ss = 0.f;
; #pragma unroll
;                 for (int bj = 0; bj < 2; ++bj)
; #pragma unroll
;                     for (int n = 0; n < 2; ++n) {
;                         const f32x4 h = bb[g & 1][bj][n] + gv[bj][n] * acc[ai][bj][m][n];
;                         *(f32x4*)(out + (size_t)row * DM + col0 + bj * 128 + n * 4) = h;
;                         ss += (h[0] * h[0] + h[1] * h[1]) + (h[2] * h[2] + h[3] * h[3]);
;                     }
;                 if (nsite < 3 * DEPTH) {
;                     ss += shx(ss, 16); ss += shx(ss, 32);
;                     if (fq == 0) __hip_atomic_store(slots + ((size_t)u.pn * M + row) * 4 + wc, ss, __ATOMIC_RELAXED, __HIP_MEMORY_SCOPE_AGENT);
.LBB0_114:
.LBB0_115:
	v_or_b32_e32 v164, 48, v208
	v_ashrrev_i32_e32 v165, 31, v164
	v_lshlrev_b64 v[166:167], 12, v[164:165]
	v_lshl_add_u64 v[142:143], v[206:207], 0, v[166:167]
	global_load_dwordx4 v[150:153], v[142:143], off offset:16
	global_load_dwordx4 v[154:157], v[142:143], off
	s_waitcnt lgkmcnt(0)
	global_load_dwordx4 v[130:133], v[142:143], off offset:528
	s_nop 0
	global_load_dwordx4 v[142:145], v[142:143], off offset:512
	v_lshl_add_u64 v[168:169], v[200:201], 0, v[212:213]
	s_waitcnt vmcnt(10)
	v_pk_fma_f32 v[32:33], v[32:33], v[202:203], v[160:161]
	v_pk_fma_f32 v[30:31], v[30:31], v[204:205], v[158:159]
	v_pk_fma_f32 v[28:29], v[28:29], v[198:199], v[148:149]
	v_pk_fma_f32 v[26:27], v[26:27], v[196:197], v[146:147]
	s_waitcnt vmcnt(8)
	v_pk_fma_f32 v[24:25], v[24:25], v[192:193], v[140:141]
	v_pk_fma_f32 v[22:23], v[22:23], v[194:195], v[138:139]
	v_pk_fma_f32 v[20:21], v[20:21], v[190:191], v[136:137]
	v_pk_fma_f32 v[18:19], v[18:19], v[188:189], v[134:135]
	s_and_b64 vcc, exec, s[4:5]
	global_store_dwordx4 v[168:169], v[30:33], off nt
	global_store_dwordx4 v[168:169], v[26:29], off offset:16 nt
	global_store_dwordx4 v[168:169], v[22:25], off offset:512 nt
	global_store_dwordx4 v[168:169], v[18:21], off offset:528 nt
	s_cbranch_vccnz .LBB0_119
	v_mul_f32_e32 v159, v31, v31
	v_mul_f32_e32 v147, v27, v27
	v_mul_f32_e32 v135, v19, v19
	v_fmac_f32_e32 v159, v30, v30
	v_mul_f32_e32 v158, v33, v33
	v_fmac_f32_e32 v147, v26, v26
	v_mul_f32_e32 v146, v29, v29
	v_mul_f32_e32 v139, v23, v23
	v_fmac_f32_e32 v135, v18, v18
	v_mul_f32_e32 v134, v21, v21
	v_fmac_f32_e32 v158, v32, v32
	v_fmac_f32_e32 v146, v28, v28
	v_fmac_f32_e32 v139, v22, v22
	v_mul_f32_e32 v138, v25, v25
	v_fmac_f32_e32 v134, v20, v20
	v_add_f32_e32 v158, v159, v158
	v_add_f32_e32 v146, v147, v146
	v_fmac_f32_e32 v138, v24, v24
	v_add_f32_e32 v134, v135, v134
	v_add_f32_e32 v146, v158, v146
	v_add_f32_e32 v138, v139, v138
	v_add_f32_e32 v138, v146, v138
	v_add_f32_e32 v134, v138, v134
	v_mov_b32_e32 v176, v134
.LBB0_118:
.LBB0_119:
	v_lshl_add_u64 v[146:147], v[200:201], 0, v[166:167]
	s_waitcnt vmcnt(6)
	v_pk_fma_f32 v[16:17], v[16:17], v[202:203], v[156:157]
	s_waitcnt lgkmcnt(0)
	v_pk_fma_f32 v[14:15], v[14:15], v[204:205], v[154:155]
	v_pk_fma_f32 v[12:13], v[12:13], v[198:199], v[152:153]
	v_pk_fma_f32 v[10:11], v[10:11], v[196:197], v[150:151]
	s_waitcnt vmcnt(4)
	v_pk_fma_f32 v[8:9], v[8:9], v[192:193], v[144:145]
	v_pk_fma_f32 v[6:7], v[6:7], v[194:195], v[142:143]
	v_pk_fma_f32 v[4:5], v[4:5], v[190:191], v[132:133]
	v_pk_fma_f32 v[2:3], v[2:3], v[188:189], v[130:131]
	s_and_b64 vcc, exec, s[4:5]
	global_store_dwordx4 v[146:147], v[14:17], off nt
	global_store_dwordx4 v[146:147], v[10:13], off offset:16 nt
	global_store_dwordx4 v[146:147], v[6:9], off offset:512 nt
	global_store_dwordx4 v[146:147], v[2:5], off offset:528 nt
	s_cbranch_vccnz .LBB0_123
	v_mul_f32_e32 v135, v15, v15
	v_fmac_f32_e32 v135, v14, v14
	v_mul_f32_e32 v134, v17, v17
	v_fmac_f32_e32 v134, v16, v16
	v_add_f32_e32 v134, v135, v134
	v_mul_f32_e32 v135, v11, v11
	v_mul_f32_e32 v136, v13, v13
	v_fmac_f32_e32 v135, v10, v10
	v_fmac_f32_e32 v136, v12, v12
	v_mul_f32_e32 v131, v3, v3
	v_add_f32_e32 v135, v135, v136
	v_fmac_f32_e32 v131, v2, v2
	v_mul_f32_e32 v130, v5, v5
	v_add_f32_e32 v134, v134, v135
	v_mul_f32_e32 v135, v7, v7
	v_mul_f32_e32 v136, v9, v9
	v_fmac_f32_e32 v130, v4, v4
	v_fmac_f32_e32 v135, v6, v6
	v_fmac_f32_e32 v136, v8, v8
	v_add_f32_e32 v130, v131, v130
	v_add_f32_e32 v135, v135, v136
	v_add_f32_e32 v134, v134, v135
	v_add_f32_e32 v130, v134, v130
	v_mov_b32_e32 v177, v130
